# attention unit epilogue rewritten in the lane=query layout (lane-local 1/l, sub-LN sums via permlane swaps, swizzled Y image; no layout conversion)
# baseline (speedup 1.0000x reference)
.LBB0_256:
	v_lshlrev_b32_e32 v0, 3, v217
	v_lshl_add_u32 v36, v0, 2, s95
	v_lshl_add_u32 v36, v218, 4, v36
	s_waitcnt vmcnt(0) lgkmcnt(0)
	s_barrier
	v_lshl_add_u32 v37, v164, 10, v36
	ds_read_b128 v[38:41], v37
	v_xor_b32_e32 v201, 16, v37
	ds_read_b128 v[42:45], v201
	s_waitcnt vmcnt(7)
	v_lshlrev_b32_e32 v37, 16, v30
	v_mul_f32_e32 v46, 0xbfb8aa3b, v37
	v_exp_f32_e32 v46, v46
	v_and_b32_e32 v30, 0xffff0000, v30
	v_lshl_add_u64 v[34:35], s[56:57], 0, v[34:35]
	v_lshl_add_u64 v[34:35], v[34:35], 0, s[4:5]
	v_add_f32_e32 v46, 1.0, v46
	v_rcp_f32_e32 v46, v46
	v_lshlrev_b32_e32 v0, 1, v0
	v_lshl_add_u64 v[34:35], v[34:35], 0, v[0:1]
	s_add_i32 s72, s72, 1
	v_mul_f32_e32 v37, v46, v37
	s_waitcnt lgkmcnt(1)
	v_mul_f32_e32 v37, v37, v38
	v_mul_f32_e32 v38, 0xbfb8aa3b, v30
	v_exp_f32_e32 v38, v38
	s_cmp_lg_u32 s72, s59
	v_add_f32_e32 v38, 1.0, v38
	v_rcp_f32_e32 v38, v38
	s_nop 0
	v_mul_f32_e32 v30, v38, v30
	v_mul_f32_e32 v30, v30, v39
	v_cvt_pk_bf16_f32 v30, v37, v30
	v_lshlrev_b32_e32 v37, 16, v31
	v_mul_f32_e32 v38, 0xbfb8aa3b, v37
	v_exp_f32_e32 v38, v38
	v_and_b32_e32 v31, 0xffff0000, v31
	v_add_f32_e32 v38, 1.0, v38
	v_rcp_f32_e32 v38, v38
	s_nop 0
	v_mul_f32_e32 v37, v38, v37
	v_mul_f32_e32 v38, 0xbfb8aa3b, v31
	v_exp_f32_e32 v38, v38
	v_mul_f32_e32 v37, v37, v40
	v_add_f32_e32 v38, 1.0, v38
	v_rcp_f32_e32 v38, v38
	s_nop 0
	v_mul_f32_e32 v31, v38, v31
	v_mul_f32_e32 v31, v31, v41
	v_cvt_pk_bf16_f32 v31, v37, v31
	v_lshlrev_b32_e32 v37, 16, v32
	v_mul_f32_e32 v38, 0xbfb8aa3b, v37
	v_exp_f32_e32 v38, v38
	v_and_b32_e32 v32, 0xffff0000, v32
	v_add_f32_e32 v38, 1.0, v38
	v_rcp_f32_e32 v38, v38
	s_nop 0
	v_mul_f32_e32 v37, v38, v37
	v_mul_f32_e32 v38, 0xbfb8aa3b, v32
	v_exp_f32_e32 v38, v38
	s_waitcnt lgkmcnt(0)
	v_mul_f32_e32 v37, v37, v42
	v_add_f32_e32 v38, 1.0, v38
	v_rcp_f32_e32 v38, v38
	s_nop 0
	v_mul_f32_e32 v32, v38, v32
	v_mul_f32_e32 v32, v32, v43
	v_cvt_pk_bf16_f32 v32, v37, v32
	v_lshlrev_b32_e32 v37, 16, v33
	v_mul_f32_e32 v38, 0xbfb8aa3b, v37
	v_exp_f32_e32 v38, v38
	v_and_b32_e32 v33, 0xffff0000, v33
	v_add_f32_e32 v38, 1.0, v38
	v_rcp_f32_e32 v38, v38
	s_nop 0
	v_mul_f32_e32 v37, v38, v37
	v_mul_f32_e32 v38, 0xbfb8aa3b, v33
	v_exp_f32_e32 v38, v38
	v_mul_f32_e32 v37, v37, v44
	v_add_f32_e32 v38, 1.0, v38
	v_rcp_f32_e32 v38, v38
	s_nop 0
	v_mul_f32_e32 v33, v38, v33
	v_mul_f32_e32 v33, v33, v45
	v_cvt_pk_bf16_f32 v33, v37, v33
	s_waitcnt vmcnt(6)
	v_lshlrev_b32_e32 v37, 16, v26
	v_mul_f32_e32 v42, 0xbfb8aa3b, v37
	v_exp_f32_e32 v42, v42
	global_store_dwordx4 v[34:35], v[30:33], off
	v_add_u32_e32 v34, 2, v164
	v_and_b32_e32 v26, 0xffff0000, v26
	v_add_f32_e32 v42, 1.0, v42
	v_xor_b32_e32 v200, 0x20, v36
	v_lshl_add_u32 v30, v34, 10, v200
	v_rcp_f32_e32 v42, v42
	ds_read_b128 v[38:41], v30
	v_xor_b32_e32 v201, 16, v30
	ds_read_b128 v[30:33], v201
	v_add_u32_e32 v34, s3, v34
	v_ashrrev_i32_e32 v35, 31, v34
	v_mul_f32_e32 v37, v42, v37
	s_waitcnt lgkmcnt(1)
	v_mul_f32_e32 v37, v37, v38
	v_mul_f32_e32 v38, 0xbfb8aa3b, v26
	v_exp_f32_e32 v38, v38
	s_nop 0
	v_add_f32_e32 v38, 1.0, v38
	v_rcp_f32_e32 v38, v38
	s_nop 0
	v_mul_f32_e32 v26, v38, v26
	v_mul_f32_e32 v26, v26, v39
	v_cvt_pk_bf16_f32 v26, v37, v26
	v_lshlrev_b32_e32 v37, 16, v27
	v_mul_f32_e32 v38, 0xbfb8aa3b, v37
	v_exp_f32_e32 v38, v38
	v_and_b32_e32 v27, 0xffff0000, v27
	v_add_f32_e32 v38, 1.0, v38
	v_rcp_f32_e32 v38, v38
	s_nop 0
	v_mul_f32_e32 v37, v38, v37
	v_mul_f32_e32 v38, 0xbfb8aa3b, v27
	v_exp_f32_e32 v38, v38
	v_mul_f32_e32 v37, v37, v40
	v_add_f32_e32 v38, 1.0, v38
	v_rcp_f32_e32 v38, v38
	s_nop 0
	v_mul_f32_e32 v27, v38, v27
	v_mul_f32_e32 v27, v27, v41
	v_cvt_pk_bf16_f32 v27, v37, v27
	v_lshlrev_b32_e32 v37, 16, v28
	v_mul_f32_e32 v38, 0xbfb8aa3b, v37
	v_exp_f32_e32 v38, v38
	v_and_b32_e32 v28, 0xffff0000, v28
	v_add_f32_e32 v38, 1.0, v38
	v_rcp_f32_e32 v38, v38
	s_nop 0
	v_mul_f32_e32 v37, v38, v37
	s_waitcnt lgkmcnt(0)
	v_mul_f32_e32 v30, v37, v30
	v_mul_f32_e32 v37, 0xbfb8aa3b, v28
	v_exp_f32_e32 v37, v37
	s_nop 0
	v_add_f32_e32 v37, 1.0, v37
	v_rcp_f32_e32 v37, v37
	s_nop 0
	v_mul_f32_e32 v28, v37, v28
	v_mul_f32_e32 v28, v28, v31
	v_cvt_pk_bf16_f32 v28, v30, v28
	v_lshlrev_b32_e32 v30, 16, v29
	v_mul_f32_e32 v31, 0xbfb8aa3b, v30
	v_exp_f32_e32 v31, v31
	v_and_b32_e32 v29, 0xffff0000, v29
	s_waitcnt vmcnt(6)
	v_lshlrev_b32_e32 v37, 16, v22
	v_mul_f32_e32 v38, 0xbfb8aa3b, v37
	v_add_f32_e32 v31, 1.0, v31
	v_rcp_f32_e32 v31, v31
	v_exp_f32_e32 v38, v38
	v_and_b32_e32 v22, 0xffff0000, v22
	v_mul_f32_e32 v30, v31, v30
	v_mul_f32_e32 v31, 0xbfb8aa3b, v29
	v_exp_f32_e32 v31, v31
	v_mul_f32_e32 v30, v30, v32
	v_add_f32_e32 v38, 1.0, v38
	v_rcp_f32_e32 v38, v38
	v_add_f32_e32 v31, 1.0, v31
	v_rcp_f32_e32 v31, v31
	v_mul_f32_e32 v37, v38, v37
	v_mul_f32_e32 v29, v31, v29
	v_mul_f32_e32 v29, v29, v33
	v_cvt_pk_bf16_f32 v29, v30, v29
	v_lshlrev_b64 v[30:31], 13, v[34:35]
	v_lshl_add_u64 v[30:31], s[56:57], 0, v[30:31]
	v_lshl_add_u64 v[30:31], v[30:31], 0, s[4:5]
	v_lshl_add_u64 v[30:31], v[30:31], 0, v[0:1]
	global_store_dwordx4 v[30:31], v[26:29], off
	v_add_u32_e32 v30, 4, v164
	s_nop 0
	v_xor_b32_e32 v200, 0x40, v36
	v_lshl_add_u32 v26, v30, 10, v200
	ds_read_b128 v[32:35], v26
	v_xor_b32_e32 v201, 16, v26
	ds_read_b128 v[26:29], v201
	v_add_u32_e32 v30, s3, v30
	v_ashrrev_i32_e32 v31, 31, v30
	s_waitcnt lgkmcnt(1)
	v_mul_f32_e32 v32, v37, v32
	v_mul_f32_e32 v37, 0xbfb8aa3b, v22
	v_exp_f32_e32 v37, v37
	s_nop 0
	v_add_f32_e32 v37, 1.0, v37
	v_rcp_f32_e32 v37, v37
	s_nop 0
	v_mul_f32_e32 v22, v37, v22
	v_mul_f32_e32 v22, v22, v33
	v_cvt_pk_bf16_f32 v22, v32, v22
	v_lshlrev_b32_e32 v32, 16, v23
	v_mul_f32_e32 v33, 0xbfb8aa3b, v32
	v_exp_f32_e32 v33, v33
	v_and_b32_e32 v23, 0xffff0000, v23
	v_add_f32_e32 v33, 1.0, v33
	v_rcp_f32_e32 v33, v33
	s_nop 0
	v_mul_f32_e32 v32, v33, v32
	v_mul_f32_e32 v33, 0xbfb8aa3b, v23
	v_exp_f32_e32 v33, v33
	v_mul_f32_e32 v32, v32, v34
	v_add_f32_e32 v33, 1.0, v33
	v_rcp_f32_e32 v33, v33
	s_nop 0
	v_mul_f32_e32 v23, v33, v23
	v_mul_f32_e32 v23, v23, v35
	v_cvt_pk_bf16_f32 v23, v32, v23
	v_lshlrev_b32_e32 v32, 16, v24
	v_mul_f32_e32 v33, 0xbfb8aa3b, v32
	v_exp_f32_e32 v33, v33
	v_and_b32_e32 v24, 0xffff0000, v24
	v_add_f32_e32 v33, 1.0, v33
	v_rcp_f32_e32 v33, v33
	s_nop 0
	v_mul_f32_e32 v32, v33, v32
	s_waitcnt lgkmcnt(0)
	v_mul_f32_e32 v26, v32, v26
	v_mul_f32_e32 v32, 0xbfb8aa3b, v24
	v_exp_f32_e32 v32, v32
	s_nop 0
	v_add_f32_e32 v32, 1.0, v32
	v_rcp_f32_e32 v32, v32
	s_nop 0
	v_mul_f32_e32 v24, v32, v24
	v_mul_f32_e32 v24, v24, v27
	v_cvt_pk_bf16_f32 v24, v26, v24
	v_lshlrev_b32_e32 v26, 16, v25
	v_mul_f32_e32 v27, 0xbfb8aa3b, v26
	v_exp_f32_e32 v27, v27
	v_and_b32_e32 v25, 0xffff0000, v25
	s_waitcnt vmcnt(6)
	v_lshlrev_b32_e32 v32, 16, v18
	v_mul_f32_e32 v33, 0xbfb8aa3b, v32
	v_add_f32_e32 v27, 1.0, v27
	v_rcp_f32_e32 v27, v27
	v_exp_f32_e32 v33, v33
	v_and_b32_e32 v18, 0xffff0000, v18
	v_mul_f32_e32 v26, v27, v26
	v_mul_f32_e32 v27, 0xbfb8aa3b, v25
	v_exp_f32_e32 v27, v27
	v_mul_f32_e32 v26, v26, v28
	v_add_f32_e32 v33, 1.0, v33
	v_rcp_f32_e32 v33, v33
	v_add_f32_e32 v27, 1.0, v27
	v_rcp_f32_e32 v27, v27
	v_mul_f32_e32 v32, v33, v32
	v_mul_f32_e32 v25, v27, v25
	v_mul_f32_e32 v25, v25, v29
	v_cvt_pk_bf16_f32 v25, v26, v25
	v_lshlrev_b64 v[26:27], 13, v[30:31]
	v_lshl_add_u64 v[26:27], s[56:57], 0, v[26:27]
	v_lshl_add_u64 v[26:27], v[26:27], 0, s[4:5]
	v_lshl_add_u64 v[26:27], v[26:27], 0, v[0:1]
	global_store_dwordx4 v[26:27], v[22:25], off
	v_add_u32_e32 v26, 6, v164
	s_nop 0
	v_xor_b32_e32 v200, 0x60, v36
	v_lshl_add_u32 v22, v26, 10, v200
	ds_read_b128 v[28:31], v22
	v_xor_b32_e32 v201, 16, v22
	ds_read_b128 v[22:25], v201
	v_add_u32_e32 v26, s3, v26
	v_ashrrev_i32_e32 v27, 31, v26
	s_waitcnt lgkmcnt(1)
	v_mul_f32_e32 v28, v32, v28
	v_mul_f32_e32 v32, 0xbfb8aa3b, v18
	v_exp_f32_e32 v32, v32
	s_nop 0
	v_add_f32_e32 v32, 1.0, v32
	v_rcp_f32_e32 v32, v32
	s_nop 0
	v_mul_f32_e32 v18, v32, v18
	v_mul_f32_e32 v18, v18, v29
	v_cvt_pk_bf16_f32 v18, v28, v18
	v_lshlrev_b32_e32 v28, 16, v19
	v_mul_f32_e32 v29, 0xbfb8aa3b, v28
	v_exp_f32_e32 v29, v29
	v_and_b32_e32 v19, 0xffff0000, v19
	v_add_f32_e32 v29, 1.0, v29
	v_rcp_f32_e32 v29, v29
	s_nop 0
	v_mul_f32_e32 v28, v29, v28
	v_mul_f32_e32 v29, 0xbfb8aa3b, v19
	v_exp_f32_e32 v29, v29
	v_mul_f32_e32 v28, v28, v30
	v_add_f32_e32 v29, 1.0, v29
	v_rcp_f32_e32 v29, v29
	s_nop 0
	v_mul_f32_e32 v19, v29, v19
	v_mul_f32_e32 v19, v19, v31
	v_cvt_pk_bf16_f32 v19, v28, v19
	v_lshlrev_b32_e32 v28, 16, v20
	v_mul_f32_e32 v29, 0xbfb8aa3b, v28
	v_exp_f32_e32 v29, v29
	v_and_b32_e32 v20, 0xffff0000, v20
	v_add_f32_e32 v29, 1.0, v29
	v_rcp_f32_e32 v29, v29
	s_nop 0
	v_mul_f32_e32 v28, v29, v28
	s_waitcnt lgkmcnt(0)
	v_mul_f32_e32 v22, v28, v22
	v_mul_f32_e32 v28, 0xbfb8aa3b, v20
	v_exp_f32_e32 v28, v28
	s_nop 0
	v_add_f32_e32 v28, 1.0, v28
	v_rcp_f32_e32 v28, v28
	s_nop 0
	v_mul_f32_e32 v20, v28, v20
	v_mul_f32_e32 v20, v20, v23
	v_cvt_pk_bf16_f32 v20, v22, v20
	v_lshlrev_b32_e32 v22, 16, v21
	v_mul_f32_e32 v23, 0xbfb8aa3b, v22
	v_exp_f32_e32 v23, v23
	v_and_b32_e32 v21, 0xffff0000, v21
	s_waitcnt vmcnt(6)
	v_lshlrev_b32_e32 v28, 16, v14
	v_mul_f32_e32 v29, 0xbfb8aa3b, v28
	v_add_f32_e32 v23, 1.0, v23
	v_rcp_f32_e32 v23, v23
	v_exp_f32_e32 v29, v29
	v_and_b32_e32 v14, 0xffff0000, v14
	v_mul_f32_e32 v22, v23, v22
	v_mul_f32_e32 v23, 0xbfb8aa3b, v21
	v_exp_f32_e32 v23, v23
	v_mul_f32_e32 v22, v22, v24
	v_add_f32_e32 v29, 1.0, v29
	v_rcp_f32_e32 v29, v29
	v_add_f32_e32 v23, 1.0, v23
	v_rcp_f32_e32 v23, v23
	v_mul_f32_e32 v28, v29, v28
	v_mul_f32_e32 v21, v23, v21
	v_mul_f32_e32 v21, v21, v25
	v_cvt_pk_bf16_f32 v21, v22, v21
	v_lshlrev_b64 v[22:23], 13, v[26:27]
	v_lshl_add_u64 v[22:23], s[56:57], 0, v[22:23]
	v_lshl_add_u64 v[22:23], v[22:23], 0, s[4:5]
	v_lshl_add_u64 v[22:23], v[22:23], 0, v[0:1]
	global_store_dwordx4 v[22:23], v[18:21], off
	v_add_u32_e32 v22, 8, v164
	s_nop 0
	v_xor_b32_e32 v200, 0x80, v36
	v_lshl_add_u32 v18, v22, 10, v200
	ds_read_b128 v[24:27], v18
	v_xor_b32_e32 v201, 16, v18
	ds_read_b128 v[18:21], v201
	v_add_u32_e32 v22, s3, v22
	v_ashrrev_i32_e32 v23, 31, v22
	s_waitcnt lgkmcnt(1)
	v_mul_f32_e32 v24, v28, v24
	v_mul_f32_e32 v28, 0xbfb8aa3b, v14
	v_exp_f32_e32 v28, v28
	s_nop 0
	v_add_f32_e32 v28, 1.0, v28
	v_rcp_f32_e32 v28, v28
	s_nop 0
	v_mul_f32_e32 v14, v28, v14
	v_mul_f32_e32 v14, v14, v25
	v_cvt_pk_bf16_f32 v14, v24, v14
	v_lshlrev_b32_e32 v24, 16, v15
	v_mul_f32_e32 v25, 0xbfb8aa3b, v24
	v_exp_f32_e32 v25, v25
	v_and_b32_e32 v15, 0xffff0000, v15
	v_add_f32_e32 v25, 1.0, v25
	v_rcp_f32_e32 v25, v25
	s_nop 0
	v_mul_f32_e32 v24, v25, v24
	v_mul_f32_e32 v25, 0xbfb8aa3b, v15
	v_exp_f32_e32 v25, v25
	v_mul_f32_e32 v24, v24, v26
	v_add_f32_e32 v25, 1.0, v25
	v_rcp_f32_e32 v25, v25
	s_nop 0
	v_mul_f32_e32 v15, v25, v15
	v_mul_f32_e32 v15, v15, v27
	v_cvt_pk_bf16_f32 v15, v24, v15
	v_lshlrev_b32_e32 v24, 16, v16
	v_mul_f32_e32 v25, 0xbfb8aa3b, v24
	v_exp_f32_e32 v25, v25
	v_and_b32_e32 v16, 0xffff0000, v16
	v_add_f32_e32 v25, 1.0, v25
	v_rcp_f32_e32 v25, v25
	s_nop 0
	v_mul_f32_e32 v24, v25, v24
	s_waitcnt lgkmcnt(0)
	v_mul_f32_e32 v18, v24, v18
	v_mul_f32_e32 v24, 0xbfb8aa3b, v16
	v_exp_f32_e32 v24, v24
	s_nop 0
	v_add_f32_e32 v24, 1.0, v24
	v_rcp_f32_e32 v24, v24
	s_nop 0
	v_mul_f32_e32 v16, v24, v16
	v_mul_f32_e32 v16, v16, v19
	v_cvt_pk_bf16_f32 v16, v18, v16
	v_lshlrev_b32_e32 v18, 16, v17
	v_mul_f32_e32 v19, 0xbfb8aa3b, v18
	v_exp_f32_e32 v19, v19
	v_and_b32_e32 v17, 0xffff0000, v17
	s_waitcnt vmcnt(6)
	v_lshlrev_b32_e32 v24, 16, v10
	v_mul_f32_e32 v25, 0xbfb8aa3b, v24
	v_add_f32_e32 v19, 1.0, v19
	v_rcp_f32_e32 v19, v19
	v_exp_f32_e32 v25, v25
	v_and_b32_e32 v10, 0xffff0000, v10
	v_mul_f32_e32 v18, v19, v18
	v_mul_f32_e32 v19, 0xbfb8aa3b, v17
	v_exp_f32_e32 v19, v19
	v_mul_f32_e32 v18, v18, v20
	v_add_f32_e32 v25, 1.0, v25
	v_rcp_f32_e32 v25, v25
	v_add_f32_e32 v19, 1.0, v19
	v_rcp_f32_e32 v19, v19
	v_mul_f32_e32 v24, v25, v24
	v_mul_f32_e32 v17, v19, v17
	v_mul_f32_e32 v17, v17, v21
	v_cvt_pk_bf16_f32 v17, v18, v17
	v_lshlrev_b64 v[18:19], 13, v[22:23]
	v_lshl_add_u64 v[18:19], s[56:57], 0, v[18:19]
	v_lshl_add_u64 v[18:19], v[18:19], 0, s[4:5]
	v_lshl_add_u64 v[18:19], v[18:19], 0, v[0:1]
	global_store_dwordx4 v[18:19], v[14:17], off
	v_add_u32_e32 v18, 10, v164
	s_nop 0
	v_xor_b32_e32 v200, 0xa0, v36
	v_lshl_add_u32 v14, v18, 10, v200
	ds_read_b128 v[20:23], v14
	v_xor_b32_e32 v201, 16, v14
	ds_read_b128 v[14:17], v201
	v_add_u32_e32 v18, s3, v18
	v_ashrrev_i32_e32 v19, 31, v18
	s_waitcnt lgkmcnt(1)
	v_mul_f32_e32 v20, v24, v20
	v_mul_f32_e32 v24, 0xbfb8aa3b, v10
	v_exp_f32_e32 v24, v24
	s_nop 0
	v_add_f32_e32 v24, 1.0, v24
	v_rcp_f32_e32 v24, v24
	s_nop 0
	v_mul_f32_e32 v10, v24, v10
	v_mul_f32_e32 v10, v10, v21
	v_cvt_pk_bf16_f32 v10, v20, v10
	v_lshlrev_b32_e32 v20, 16, v11
	v_mul_f32_e32 v21, 0xbfb8aa3b, v20
	v_exp_f32_e32 v21, v21
	v_and_b32_e32 v11, 0xffff0000, v11
	v_add_f32_e32 v21, 1.0, v21
	v_rcp_f32_e32 v21, v21
	s_nop 0
	v_mul_f32_e32 v20, v21, v20
	v_mul_f32_e32 v21, 0xbfb8aa3b, v11
	v_exp_f32_e32 v21, v21
	v_mul_f32_e32 v20, v20, v22
	v_add_f32_e32 v21, 1.0, v21
	v_rcp_f32_e32 v21, v21
	s_nop 0
	v_mul_f32_e32 v11, v21, v11
	v_mul_f32_e32 v11, v11, v23
	v_cvt_pk_bf16_f32 v11, v20, v11
	v_lshlrev_b32_e32 v20, 16, v12
	v_mul_f32_e32 v21, 0xbfb8aa3b, v20
	v_exp_f32_e32 v21, v21
	v_and_b32_e32 v12, 0xffff0000, v12
	v_add_f32_e32 v21, 1.0, v21
	v_rcp_f32_e32 v21, v21
	s_nop 0
	v_mul_f32_e32 v20, v21, v20
	s_waitcnt lgkmcnt(0)
	v_mul_f32_e32 v14, v20, v14
	v_mul_f32_e32 v20, 0xbfb8aa3b, v12
	v_exp_f32_e32 v20, v20
	s_nop 0
	v_add_f32_e32 v20, 1.0, v20
	v_rcp_f32_e32 v20, v20
	s_nop 0
	v_mul_f32_e32 v12, v20, v12
	v_mul_f32_e32 v12, v12, v15
	v_cvt_pk_bf16_f32 v12, v14, v12
	v_lshlrev_b32_e32 v14, 16, v13
	v_mul_f32_e32 v15, 0xbfb8aa3b, v14
	v_exp_f32_e32 v15, v15
	v_and_b32_e32 v13, 0xffff0000, v13
	s_waitcnt vmcnt(6)
	v_lshlrev_b32_e32 v20, 16, v6
	v_mul_f32_e32 v21, 0xbfb8aa3b, v20
	v_add_f32_e32 v15, 1.0, v15
	v_rcp_f32_e32 v15, v15
	v_exp_f32_e32 v21, v21
	v_and_b32_e32 v6, 0xffff0000, v6
	v_mul_f32_e32 v14, v15, v14
	v_mul_f32_e32 v15, 0xbfb8aa3b, v13
	v_exp_f32_e32 v15, v15
	v_mul_f32_e32 v14, v14, v16
	v_add_f32_e32 v21, 1.0, v21
	v_rcp_f32_e32 v21, v21
	v_add_f32_e32 v15, 1.0, v15
	v_rcp_f32_e32 v15, v15
	v_mul_f32_e32 v20, v21, v20
	v_mul_f32_e32 v13, v15, v13
	v_mul_f32_e32 v13, v13, v17
	v_cvt_pk_bf16_f32 v13, v14, v13
	v_lshlrev_b64 v[14:15], 13, v[18:19]
	v_lshl_add_u64 v[14:15], s[56:57], 0, v[14:15]
	v_lshl_add_u64 v[14:15], v[14:15], 0, s[4:5]
	v_lshl_add_u64 v[14:15], v[14:15], 0, v[0:1]
	global_store_dwordx4 v[14:15], v[10:13], off
	v_add_u32_e32 v14, 12, v164
	s_nop 0
	v_xor_b32_e32 v200, 0xc0, v36
	v_lshl_add_u32 v10, v14, 10, v200
	ds_read_b128 v[16:19], v10
	v_xor_b32_e32 v201, 16, v10
	ds_read_b128 v[10:13], v201
	v_add_u32_e32 v14, s3, v14
	v_ashrrev_i32_e32 v15, 31, v14
	s_waitcnt lgkmcnt(1)
	v_mul_f32_e32 v16, v20, v16
	v_mul_f32_e32 v20, 0xbfb8aa3b, v6
	v_exp_f32_e32 v20, v20
	s_nop 0
	v_add_f32_e32 v20, 1.0, v20
	v_rcp_f32_e32 v20, v20
	s_nop 0
	v_mul_f32_e32 v6, v20, v6
	v_mul_f32_e32 v6, v6, v17
	v_cvt_pk_bf16_f32 v6, v16, v6
	v_lshlrev_b32_e32 v16, 16, v7
	v_mul_f32_e32 v17, 0xbfb8aa3b, v16
	v_exp_f32_e32 v17, v17
	v_and_b32_e32 v7, 0xffff0000, v7
	v_add_f32_e32 v17, 1.0, v17
	v_rcp_f32_e32 v17, v17
	s_nop 0
	v_mul_f32_e32 v16, v17, v16
	v_mul_f32_e32 v17, 0xbfb8aa3b, v7
	v_exp_f32_e32 v17, v17
	v_mul_f32_e32 v16, v16, v18
	v_add_f32_e32 v17, 1.0, v17
	v_rcp_f32_e32 v17, v17
	s_nop 0
	v_mul_f32_e32 v7, v17, v7
	v_mul_f32_e32 v7, v7, v19
	v_cvt_pk_bf16_f32 v7, v16, v7
	v_lshlrev_b32_e32 v16, 16, v8
	v_mul_f32_e32 v17, 0xbfb8aa3b, v16
	v_exp_f32_e32 v17, v17
	v_and_b32_e32 v8, 0xffff0000, v8
	v_add_f32_e32 v17, 1.0, v17
	v_rcp_f32_e32 v17, v17
	s_nop 0
	v_mul_f32_e32 v16, v17, v16
	s_waitcnt lgkmcnt(0)
	v_mul_f32_e32 v10, v16, v10
	v_mul_f32_e32 v16, 0xbfb8aa3b, v8
	v_exp_f32_e32 v16, v16
	s_nop 0
	v_add_f32_e32 v16, 1.0, v16
	v_rcp_f32_e32 v16, v16
	s_nop 0
	v_mul_f32_e32 v8, v16, v8
	v_mul_f32_e32 v8, v8, v11
	v_cvt_pk_bf16_f32 v8, v10, v8
	v_lshlrev_b32_e32 v10, 16, v9
	v_mul_f32_e32 v11, 0xbfb8aa3b, v10
	v_exp_f32_e32 v11, v11
	v_and_b32_e32 v9, 0xffff0000, v9
	s_waitcnt vmcnt(6)
	v_lshlrev_b32_e32 v16, 16, v2
	v_mul_f32_e32 v17, 0xbfb8aa3b, v16
	v_add_f32_e32 v11, 1.0, v11
	v_rcp_f32_e32 v11, v11
	v_exp_f32_e32 v17, v17
	v_and_b32_e32 v2, 0xffff0000, v2
	v_mul_f32_e32 v10, v11, v10
	v_mul_f32_e32 v11, 0xbfb8aa3b, v9
	v_exp_f32_e32 v11, v11
	v_mul_f32_e32 v10, v10, v12
	v_add_f32_e32 v17, 1.0, v17
	v_rcp_f32_e32 v17, v17
	v_add_f32_e32 v11, 1.0, v11
	v_rcp_f32_e32 v11, v11
	v_mul_f32_e32 v16, v17, v16
	v_mul_f32_e32 v9, v11, v9
	v_mul_f32_e32 v9, v9, v13
	v_cvt_pk_bf16_f32 v9, v10, v9
	v_lshlrev_b64 v[10:11], 13, v[14:15]
	v_lshl_add_u64 v[10:11], s[56:57], 0, v[10:11]
	v_lshl_add_u64 v[10:11], v[10:11], 0, s[4:5]
	v_lshl_add_u64 v[10:11], v[10:11], 0, v[0:1]
	global_store_dwordx4 v[10:11], v[6:9], off
	v_add_u32_e32 v10, 14, v164
	s_nop 0
	v_xor_b32_e32 v200, 0xe0, v36
	v_lshl_add_u32 v6, v10, 10, v200
	ds_read_b128 v[12:15], v6
	v_xor_b32_e32 v201, 16, v6
	ds_read_b128 v[6:9], v201
	v_add_u32_e32 v10, s3, v10
	v_ashrrev_i32_e32 v11, 31, v10
	s_waitcnt lgkmcnt(1)
	v_mul_f32_e32 v12, v16, v12
	v_mul_f32_e32 v16, 0xbfb8aa3b, v2
	v_exp_f32_e32 v16, v16
	s_nop 0
	v_add_f32_e32 v16, 1.0, v16
	v_rcp_f32_e32 v16, v16
	s_nop 0
	v_mul_f32_e32 v2, v16, v2
	v_mul_f32_e32 v2, v2, v13
	v_cvt_pk_bf16_f32 v2, v12, v2
	v_lshlrev_b32_e32 v12, 16, v3
	v_mul_f32_e32 v13, 0xbfb8aa3b, v12
	v_exp_f32_e32 v13, v13
	v_and_b32_e32 v3, 0xffff0000, v3
	v_add_f32_e32 v13, 1.0, v13
	v_rcp_f32_e32 v13, v13
	s_nop 0
	v_mul_f32_e32 v12, v13, v12
	v_mul_f32_e32 v13, 0xbfb8aa3b, v3
	v_exp_f32_e32 v13, v13
	v_mul_f32_e32 v12, v12, v14
	v_add_f32_e32 v13, 1.0, v13
	v_rcp_f32_e32 v13, v13
	s_nop 0
	v_mul_f32_e32 v3, v13, v3
	v_mul_f32_e32 v3, v3, v15
	v_cvt_pk_bf16_f32 v3, v12, v3
	v_lshlrev_b32_e32 v12, 16, v4
	v_mul_f32_e32 v13, 0xbfb8aa3b, v12
	v_exp_f32_e32 v13, v13
	v_and_b32_e32 v4, 0xffff0000, v4
	v_add_f32_e32 v13, 1.0, v13
	v_rcp_f32_e32 v13, v13
	s_nop 0
	v_mul_f32_e32 v12, v13, v12
	s_waitcnt lgkmcnt(0)
	v_mul_f32_e32 v6, v12, v6
	v_mul_f32_e32 v12, 0xbfb8aa3b, v4
	v_exp_f32_e32 v12, v12
	s_nop 0
	v_add_f32_e32 v12, 1.0, v12
	v_rcp_f32_e32 v12, v12
	s_nop 0
	v_mul_f32_e32 v4, v12, v4
	v_mul_f32_e32 v4, v4, v7
	v_cvt_pk_bf16_f32 v4, v6, v4
	v_lshlrev_b32_e32 v6, 16, v5
	v_mul_f32_e32 v7, 0xbfb8aa3b, v6
	v_exp_f32_e32 v7, v7
	v_and_b32_e32 v5, 0xffff0000, v5
	v_add_f32_e32 v7, 1.0, v7
	v_rcp_f32_e32 v7, v7
	s_nop 0
	v_mul_f32_e32 v6, v7, v6
	v_mul_f32_e32 v7, 0xbfb8aa3b, v5
	v_exp_f32_e32 v7, v7
	v_mul_f32_e32 v6, v6, v8
	v_add_f32_e32 v7, 1.0, v7
	v_rcp_f32_e32 v7, v7
	s_nop 0
	v_mul_f32_e32 v5, v7, v5
	v_mul_f32_e32 v5, v5, v9
	v_cvt_pk_bf16_f32 v5, v6, v5
	v_lshlrev_b64 v[6:7], 13, v[10:11]
	v_lshl_add_u64 v[6:7], s[56:57], 0, v[6:7]
	v_lshl_add_u64 v[6:7], v[6:7], 0, s[4:5]
	v_lshl_add_u64 v[6:7], v[6:7], 0, v[0:1]
	global_store_dwordx4 v[6:7], v[2:5], off
	s_waitcnt vmcnt(0) lgkmcnt(0)
	s_barrier
	s_cbranch_scc0 .LBB0_359

.Lat_end_b:
.Lat_done:
	s_waitcnt lgkmcnt(0)
	s_barrier
	s_mov_b32 m0, s92
	s_nop 1
	v_permlane16_swap_b32_e32 v232, v244
	v_add_f32_e32 v232, v232, v244
	v_mov_b32_e32 v244, v232
	s_nop 1
	v_permlane32_swap_b32_e32 v232, v244
	v_add_f32_e32 v232, v232, v244
	v_mov_b32_e32 v244, v232
	s_nop 1
	v_permlane16_swap_b32_e32 v232, v244
	s_nop 0
	v_div_scale_f32 v162, s[6:7], v232, v232, 1.0
	v_rcp_f32_e32 v163, v162
	v_div_scale_f32 v164, vcc, 1.0, v232, 1.0
	v_fma_f32 v165, -v162, v163, 1.0
	v_fmac_f32_e32 v163, v165, v163
	v_mul_f32_e32 v165, v164, v163
	v_fma_f32 v166, -v162, v165, v164
	v_fmac_f32_e32 v165, v166, v163
	v_fma_f32 v162, -v162, v165, v164
	v_div_fmas_f32 v162, v162, v163, v165
	v_div_fixup_f32 v232, v162, v232, 1.0
	v_div_scale_f32 v167, s[6:7], v244, v244, 1.0
	v_rcp_f32_e32 v168, v167
	v_div_scale_f32 v169, vcc, 1.0, v244, 1.0
	v_fma_f32 v170, -v167, v168, 1.0
	v_fmac_f32_e32 v168, v170, v168
	v_mul_f32_e32 v170, v169, v168
	v_fma_f32 v171, -v167, v170, v169
	v_fmac_f32_e32 v170, v171, v168
	v_fma_f32 v167, -v167, v170, v169
	v_div_fmas_f32 v167, v167, v168, v170
	v_div_fixup_f32 v244, v167, v244, 1.0
	v_readlane_b32 s4, v254, 27
	s_nop 1
	v_add_u32_e32 v248, s4, v218
	v_add_u32_e32 v248, s3, v248
	v_lshlrev_b32_e32 v249, 13, v248
	v_lshl_add_u32 v249, v217, 4, v249
	s_lshl_b64 s[4:5], s[82:83], 1
	s_add_u32 s6, s48, s4
	s_addc_u32 s7, s49, s5
	global_load_dwordx4 v[130:133], v249, s[6:7]
	v_add_u32_e32 v249, 0x4000, v249
	global_load_dwordx4 v[134:137], v249, s[6:7]
	v_add_u32_e32 v249, 0x4000, v249
	global_load_dwordx4 v[138:141], v249, s[6:7]
	v_add_u32_e32 v249, 0x4000, v249
	global_load_dwordx4 v[142:145], v249, s[6:7]
	v_add_u32_e32 v249, 0x4000, v249
	global_load_dwordx4 v[146:149], v249, s[6:7]
	v_add_u32_e32 v249, 0x4000, v249
	global_load_dwordx4 v[150:153], v249, s[6:7]
	v_add_u32_e32 v249, 0x4000, v249
	global_load_dwordx4 v[154:157], v249, s[6:7]
	v_add_u32_e32 v249, 0x4000, v249
	global_load_dwordx4 v[158:161], v249, s[6:7]
	v_mul_f32_e32 v114, v114, v232
	v_mul_f32_e32 v115, v115, v232
	v_mul_f32_e32 v116, v116, v232
	v_mul_f32_e32 v117, v117, v232
	v_mul_f32_e32 v118, v118, v232
	v_mul_f32_e32 v119, v119, v232
	v_mul_f32_e32 v120, v120, v232
	v_mul_f32_e32 v121, v121, v232
	v_mul_f32_e32 v98, v98, v232
	v_mul_f32_e32 v99, v99, v232
	v_mul_f32_e32 v100, v100, v232
	v_mul_f32_e32 v101, v101, v232
	v_mul_f32_e32 v102, v102, v232
	v_mul_f32_e32 v103, v103, v232
	v_mul_f32_e32 v104, v104, v232
	v_mul_f32_e32 v105, v105, v232
	v_mul_f32_e32 v82, v82, v232
	v_mul_f32_e32 v83, v83, v232
	v_mul_f32_e32 v84, v84, v232
	v_mul_f32_e32 v85, v85, v232
	v_mul_f32_e32 v86, v86, v232
	v_mul_f32_e32 v87, v87, v232
	v_mul_f32_e32 v88, v88, v232
	v_mul_f32_e32 v89, v89, v232
	v_mul_f32_e32 v66, v66, v232
	v_mul_f32_e32 v67, v67, v232
	v_mul_f32_e32 v68, v68, v232
	v_mul_f32_e32 v69, v69, v232
	v_mul_f32_e32 v70, v70, v232
	v_mul_f32_e32 v71, v71, v232
	v_mul_f32_e32 v72, v72, v232
	v_mul_f32_e32 v73, v73, v232
	v_mul_f32_e32 v50, v50, v232
	v_mul_f32_e32 v51, v51, v232
	v_mul_f32_e32 v52, v52, v232
	v_mul_f32_e32 v53, v53, v232
	v_mul_f32_e32 v54, v54, v232
	v_mul_f32_e32 v55, v55, v232
	v_mul_f32_e32 v56, v56, v232
	v_mul_f32_e32 v57, v57, v232
	v_mul_f32_e32 v34, v34, v232
	v_mul_f32_e32 v35, v35, v232
	v_mul_f32_e32 v36, v36, v232
	v_mul_f32_e32 v37, v37, v232
	v_mul_f32_e32 v38, v38, v232
	v_mul_f32_e32 v39, v39, v232
	v_mul_f32_e32 v40, v40, v232
	v_mul_f32_e32 v41, v41, v232
	v_mul_f32_e32 v18, v18, v232
	v_mul_f32_e32 v19, v19, v232
	v_mul_f32_e32 v20, v20, v232
	v_mul_f32_e32 v21, v21, v232
	v_mul_f32_e32 v22, v22, v232
	v_mul_f32_e32 v23, v23, v232
	v_mul_f32_e32 v24, v24, v232
	v_mul_f32_e32 v25, v25, v232
	v_mul_f32_e32 v2, v2, v232
	v_mul_f32_e32 v3, v3, v232
	v_mul_f32_e32 v4, v4, v232
	v_mul_f32_e32 v5, v5, v232
	v_mul_f32_e32 v6, v6, v232
	v_mul_f32_e32 v7, v7, v232
	v_mul_f32_e32 v8, v8, v232
	v_mul_f32_e32 v9, v9, v232
	v_mul_f32_e32 v122, v122, v244
	v_mul_f32_e32 v123, v123, v244
	v_mul_f32_e32 v124, v124, v244
	v_mul_f32_e32 v125, v125, v244
	v_mul_f32_e32 v126, v126, v244
	v_mul_f32_e32 v127, v127, v244
	v_mul_f32_e32 v128, v128, v244
	v_mul_f32_e32 v129, v129, v244
	v_mul_f32_e32 v106, v106, v244
	v_mul_f32_e32 v107, v107, v244
	v_mul_f32_e32 v108, v108, v244
	v_mul_f32_e32 v109, v109, v244
	v_mul_f32_e32 v110, v110, v244
	v_mul_f32_e32 v111, v111, v244
	v_mul_f32_e32 v112, v112, v244
	v_mul_f32_e32 v113, v113, v244
	v_mul_f32_e32 v90, v90, v244
	v_mul_f32_e32 v91, v91, v244
	v_mul_f32_e32 v92, v92, v244
	v_mul_f32_e32 v93, v93, v244
	v_mul_f32_e32 v94, v94, v244
	v_mul_f32_e32 v95, v95, v244
	v_mul_f32_e32 v96, v96, v244
	v_mul_f32_e32 v97, v97, v244
	v_mul_f32_e32 v74, v74, v244
	v_mul_f32_e32 v75, v75, v244
	v_mul_f32_e32 v76, v76, v244
	v_mul_f32_e32 v77, v77, v244
	v_mul_f32_e32 v78, v78, v244
	v_mul_f32_e32 v79, v79, v244
	v_mul_f32_e32 v80, v80, v244
	v_mul_f32_e32 v81, v81, v244
	v_mul_f32_e32 v58, v58, v244
	v_mul_f32_e32 v59, v59, v244
	v_mul_f32_e32 v60, v60, v244
	v_mul_f32_e32 v61, v61, v244
	v_mul_f32_e32 v62, v62, v244
	v_mul_f32_e32 v63, v63, v244
	v_mul_f32_e32 v64, v64, v244
	v_mul_f32_e32 v65, v65, v244
	v_mul_f32_e32 v42, v42, v244
	v_mul_f32_e32 v43, v43, v244
	v_mul_f32_e32 v44, v44, v244
	v_mul_f32_e32 v45, v45, v244
	v_mul_f32_e32 v46, v46, v244
	v_mul_f32_e32 v47, v47, v244
	v_mul_f32_e32 v48, v48, v244
	v_mul_f32_e32 v49, v49, v244
	v_mul_f32_e32 v26, v26, v244
	v_mul_f32_e32 v27, v27, v244
	v_mul_f32_e32 v28, v28, v244
	v_mul_f32_e32 v29, v29, v244
	v_mul_f32_e32 v30, v30, v244
	v_mul_f32_e32 v31, v31, v244
	v_mul_f32_e32 v32, v32, v244
	v_mul_f32_e32 v33, v33, v244
	v_mul_f32_e32 v10, v10, v244
	v_mul_f32_e32 v11, v11, v244
	v_mul_f32_e32 v12, v12, v244
	v_mul_f32_e32 v13, v13, v244
	v_mul_f32_e32 v14, v14, v244
	v_mul_f32_e32 v15, v15, v244
	v_mul_f32_e32 v16, v16, v244
	v_mul_f32_e32 v17, v17, v244
	s_cmp_lg_u64 s[0:1], 0
	s_cbranch_scc1 .Lat_ep_k
	v_mul_f32_e32 v114, v114, v210
	v_mul_f32_e32 v115, v115, v210
	v_mul_f32_e32 v116, v116, v210
	v_mul_f32_e32 v117, v117, v210
	v_mul_f32_e32 v118, v118, v210
	v_mul_f32_e32 v119, v119, v210
	v_mul_f32_e32 v120, v120, v210
	v_mul_f32_e32 v121, v121, v210
	v_mul_f32_e32 v98, v98, v210
	v_mul_f32_e32 v99, v99, v210
	v_mul_f32_e32 v100, v100, v210
	v_mul_f32_e32 v101, v101, v210
	v_mul_f32_e32 v102, v102, v210
	v_mul_f32_e32 v103, v103, v210
	v_mul_f32_e32 v104, v104, v210
	v_mul_f32_e32 v105, v105, v210
	v_mul_f32_e32 v82, v82, v210
	v_mul_f32_e32 v83, v83, v210
	v_mul_f32_e32 v84, v84, v210
	v_mul_f32_e32 v85, v85, v210
	v_mul_f32_e32 v86, v86, v210
	v_mul_f32_e32 v87, v87, v210
	v_mul_f32_e32 v88, v88, v210
	v_mul_f32_e32 v89, v89, v210
	v_mul_f32_e32 v66, v66, v210
	v_mul_f32_e32 v67, v67, v210
	v_mul_f32_e32 v68, v68, v210
	v_mul_f32_e32 v69, v69, v210
	v_mul_f32_e32 v70, v70, v210
	v_mul_f32_e32 v71, v71, v210
	v_mul_f32_e32 v72, v72, v210
	v_mul_f32_e32 v73, v73, v210
	v_mul_f32_e32 v50, v50, v210
	v_mul_f32_e32 v51, v51, v210
	v_mul_f32_e32 v52, v52, v210
	v_mul_f32_e32 v53, v53, v210
	v_mul_f32_e32 v54, v54, v210
	v_mul_f32_e32 v55, v55, v210
	v_mul_f32_e32 v56, v56, v210
	v_mul_f32_e32 v57, v57, v210
	v_mul_f32_e32 v34, v34, v210
	v_mul_f32_e32 v35, v35, v210
	v_mul_f32_e32 v36, v36, v210
	v_mul_f32_e32 v37, v37, v210
	v_mul_f32_e32 v38, v38, v210
	v_mul_f32_e32 v39, v39, v210
	v_mul_f32_e32 v40, v40, v210
	v_mul_f32_e32 v41, v41, v210
	v_mul_f32_e32 v18, v18, v210
	v_mul_f32_e32 v19, v19, v210
	v_mul_f32_e32 v20, v20, v210
	v_mul_f32_e32 v21, v21, v210
	v_mul_f32_e32 v22, v22, v210
	v_mul_f32_e32 v23, v23, v210
	v_mul_f32_e32 v24, v24, v210
	v_mul_f32_e32 v25, v25, v210
	v_mul_f32_e32 v2, v2, v210
	v_mul_f32_e32 v3, v3, v210
	v_mul_f32_e32 v4, v4, v210
	v_mul_f32_e32 v5, v5, v210
	v_mul_f32_e32 v6, v6, v210
	v_mul_f32_e32 v7, v7, v210
	v_mul_f32_e32 v8, v8, v210
	v_mul_f32_e32 v9, v9, v210
	v_mul_f32_e32 v122, v122, v210
	v_mul_f32_e32 v123, v123, v210
	v_mul_f32_e32 v124, v124, v210
	v_mul_f32_e32 v125, v125, v210
	v_mul_f32_e32 v126, v126, v210
	v_mul_f32_e32 v127, v127, v210
	v_mul_f32_e32 v128, v128, v210
	v_mul_f32_e32 v129, v129, v210
	v_mul_f32_e32 v106, v106, v210
	v_mul_f32_e32 v107, v107, v210
	v_mul_f32_e32 v108, v108, v210
	v_mul_f32_e32 v109, v109, v210
	v_mul_f32_e32 v110, v110, v210
	v_mul_f32_e32 v111, v111, v210
	v_mul_f32_e32 v112, v112, v210
	v_mul_f32_e32 v113, v113, v210
	v_mul_f32_e32 v90, v90, v210
	v_mul_f32_e32 v91, v91, v210
	v_mul_f32_e32 v92, v92, v210
	v_mul_f32_e32 v93, v93, v210
	v_mul_f32_e32 v94, v94, v210
	v_mul_f32_e32 v95, v95, v210
	v_mul_f32_e32 v96, v96, v210
	v_mul_f32_e32 v97, v97, v210
	v_mul_f32_e32 v74, v74, v210
	v_mul_f32_e32 v75, v75, v210
	v_mul_f32_e32 v76, v76, v210
	v_mul_f32_e32 v77, v77, v210
	v_mul_f32_e32 v78, v78, v210
	v_mul_f32_e32 v79, v79, v210
	v_mul_f32_e32 v80, v80, v210
	v_mul_f32_e32 v81, v81, v210
	v_mul_f32_e32 v58, v58, v210
	v_mul_f32_e32 v59, v59, v210
	v_mul_f32_e32 v60, v60, v210
	v_mul_f32_e32 v61, v61, v210
	v_mul_f32_e32 v62, v62, v210
	v_mul_f32_e32 v63, v63, v210
	v_mul_f32_e32 v64, v64, v210
	v_mul_f32_e32 v65, v65, v210
	v_mul_f32_e32 v42, v42, v210
	v_mul_f32_e32 v43, v43, v210
	v_mul_f32_e32 v44, v44, v210
	v_mul_f32_e32 v45, v45, v210
	v_mul_f32_e32 v46, v46, v210
	v_mul_f32_e32 v47, v47, v210
	v_mul_f32_e32 v48, v48, v210
	v_mul_f32_e32 v49, v49, v210
	v_mul_f32_e32 v26, v26, v210
	v_mul_f32_e32 v27, v27, v210
	v_mul_f32_e32 v28, v28, v210
	v_mul_f32_e32 v29, v29, v210
	v_mul_f32_e32 v30, v30, v210
	v_mul_f32_e32 v31, v31, v210
	v_mul_f32_e32 v32, v32, v210
	v_mul_f32_e32 v33, v33, v210
	v_mul_f32_e32 v10, v10, v210
	v_mul_f32_e32 v11, v11, v210
	v_mul_f32_e32 v12, v12, v210
	v_mul_f32_e32 v13, v13, v210
	v_mul_f32_e32 v14, v14, v210
	v_mul_f32_e32 v15, v15, v210
	v_mul_f32_e32 v16, v16, v210
	v_mul_f32_e32 v17, v17, v210
	v_lshl_add_u32 v250, v211, 4, s95
	ds_write_b128 v250, v[114:117]
	ds_write_b128 v250, v[118:121] offset:1024
	ds_write_b128 v250, v[98:101] offset:2048
	ds_write_b128 v250, v[102:105] offset:3072
	ds_write_b128 v250, v[82:85] offset:4096
	ds_write_b128 v250, v[86:89] offset:5120
	ds_write_b128 v250, v[66:69] offset:6144
	ds_write_b128 v250, v[70:73] offset:7168
	ds_write_b128 v250, v[50:53] offset:8192
	ds_write_b128 v250, v[54:57] offset:9216
	ds_write_b128 v250, v[34:37] offset:10240
	ds_write_b128 v250, v[38:41] offset:11264
	ds_write_b128 v250, v[18:21] offset:12288
	ds_write_b128 v250, v[22:25] offset:13312
	ds_write_b128 v250, v[2:5] offset:14336
	ds_write_b128 v250, v[6:9] offset:15360
	ds_write_b128 v250, v[122:125] offset:16384
	ds_write_b128 v250, v[126:129] offset:17408
	ds_write_b128 v250, v[106:109] offset:18432
	ds_write_b128 v250, v[110:113] offset:19456
	ds_write_b128 v250, v[90:93] offset:20480
	ds_write_b128 v250, v[94:97] offset:21504
	ds_write_b128 v250, v[74:77] offset:22528
	ds_write_b128 v250, v[78:81] offset:23552
	ds_write_b128 v250, v[58:61] offset:24576
	ds_write_b128 v250, v[62:65] offset:25600
	ds_write_b128 v250, v[42:45] offset:26624
	ds_write_b128 v250, v[46:49] offset:27648
	ds_write_b128 v250, v[26:29] offset:28672
	ds_write_b128 v250, v[30:33] offset:29696
	ds_write_b128 v250, v[10:13] offset:30720
	ds_write_b128 v250, v[14:17] offset:31744
	s_waitcnt lgkmcnt(0)
	s_barrier
	s_branch .Lat_ep_fin
.Lat_ep_k:
	v_and_b32_e32 v252, 0x30, v211
	global_load_dwordx4 v[194:197], v252, s[52:53] offset:512
	global_load_dwordx4 v[198:201], v252, s[52:53] offset:576
	global_load_dwordx4 v[202:205], v252, s[52:53] offset:640
	global_load_dwordx4 v[206:209], v252, s[52:53] offset:704
	global_load_dwordx4 v[232:235], v252, s[52:53] offset:768
	global_load_dwordx4 v[236:239], v252, s[52:53] offset:832
	global_load_dwordx4 v[240:243], v252, s[52:53] offset:896
	global_load_dwordx4 v[244:247], v252, s[52:53] offset:960
	v_lshl_add_u32 v250, v211, 4, s95
	s_barrier
	ds_read_b128 v[162:165], v250
	ds_read_b128 v[166:169], v250 offset:1024
	ds_read_b128 v[170:173], v250 offset:2048
	ds_read_b128 v[174:177], v250 offset:3072
	ds_read_b128 v[178:181], v250 offset:4096
	ds_read_b128 v[182:185], v250 offset:5120
	ds_read_b128 v[186:189], v250 offset:6144
	ds_read_b128 v[190:193], v250 offset:7168
	s_waitcnt lgkmcnt(7)
	v_add_f32_e32 v114, v114, v162
	v_add_f32_e32 v115, v115, v163
	v_add_f32_e32 v116, v116, v164
	v_add_f32_e32 v117, v117, v165
	ds_read_b128 v[162:165], v250 offset:8192
	s_waitcnt lgkmcnt(7)
	v_add_f32_e32 v118, v118, v166
	v_add_f32_e32 v119, v119, v167
	v_add_f32_e32 v120, v120, v168
	v_add_f32_e32 v121, v121, v169
	ds_read_b128 v[166:169], v250 offset:9216
	s_waitcnt lgkmcnt(7)
	v_add_f32_e32 v98, v98, v170
	v_add_f32_e32 v99, v99, v171
	v_add_f32_e32 v100, v100, v172
	v_add_f32_e32 v101, v101, v173
	ds_read_b128 v[170:173], v250 offset:10240
	s_waitcnt lgkmcnt(7)
	v_add_f32_e32 v102, v102, v174
	v_add_f32_e32 v103, v103, v175
	v_add_f32_e32 v104, v104, v176
	v_add_f32_e32 v105, v105, v177
	ds_read_b128 v[174:177], v250 offset:11264
	s_waitcnt lgkmcnt(7)
	v_add_f32_e32 v82, v82, v178
	v_add_f32_e32 v83, v83, v179
	v_add_f32_e32 v84, v84, v180
	v_add_f32_e32 v85, v85, v181
	ds_read_b128 v[178:181], v250 offset:12288
	s_waitcnt lgkmcnt(7)
	v_add_f32_e32 v86, v86, v182
	v_add_f32_e32 v87, v87, v183
	v_add_f32_e32 v88, v88, v184
	v_add_f32_e32 v89, v89, v185
	ds_read_b128 v[182:185], v250 offset:13312
	s_waitcnt lgkmcnt(7)
	v_add_f32_e32 v66, v66, v186
	v_add_f32_e32 v67, v67, v187
	v_add_f32_e32 v68, v68, v188
	v_add_f32_e32 v69, v69, v189
	ds_read_b128 v[186:189], v250 offset:14336
	s_waitcnt lgkmcnt(7)
	v_add_f32_e32 v70, v70, v190
	v_add_f32_e32 v71, v71, v191
	v_add_f32_e32 v72, v72, v192
	v_add_f32_e32 v73, v73, v193
	ds_read_b128 v[190:193], v250 offset:15360
	s_waitcnt lgkmcnt(7)
	v_add_f32_e32 v50, v50, v162
	v_add_f32_e32 v51, v51, v163
	v_add_f32_e32 v52, v52, v164
	v_add_f32_e32 v53, v53, v165
	ds_read_b128 v[162:165], v250 offset:16384
	s_waitcnt lgkmcnt(7)
	v_add_f32_e32 v54, v54, v166
	v_add_f32_e32 v55, v55, v167
	v_add_f32_e32 v56, v56, v168
	v_add_f32_e32 v57, v57, v169
	ds_read_b128 v[166:169], v250 offset:17408
	s_waitcnt lgkmcnt(7)
	v_add_f32_e32 v34, v34, v170
	v_add_f32_e32 v35, v35, v171
	v_add_f32_e32 v36, v36, v172
	v_add_f32_e32 v37, v37, v173
	ds_read_b128 v[170:173], v250 offset:18432
	s_waitcnt lgkmcnt(7)
	v_add_f32_e32 v38, v38, v174
	v_add_f32_e32 v39, v39, v175
	v_add_f32_e32 v40, v40, v176
	v_add_f32_e32 v41, v41, v177
	ds_read_b128 v[174:177], v250 offset:19456
	s_waitcnt lgkmcnt(7)
	v_add_f32_e32 v18, v18, v178
	v_add_f32_e32 v19, v19, v179
	v_add_f32_e32 v20, v20, v180
	v_add_f32_e32 v21, v21, v181
	ds_read_b128 v[178:181], v250 offset:20480
	s_waitcnt lgkmcnt(7)
	v_add_f32_e32 v22, v22, v182
	v_add_f32_e32 v23, v23, v183
	v_add_f32_e32 v24, v24, v184
	v_add_f32_e32 v25, v25, v185
	ds_read_b128 v[182:185], v250 offset:21504
	s_waitcnt lgkmcnt(7)
	v_add_f32_e32 v2, v2, v186
	v_add_f32_e32 v3, v3, v187
	v_add_f32_e32 v4, v4, v188
	v_add_f32_e32 v5, v5, v189
	ds_read_b128 v[186:189], v250 offset:22528
	s_waitcnt lgkmcnt(7)
	v_add_f32_e32 v6, v6, v190
	v_add_f32_e32 v7, v7, v191
	v_add_f32_e32 v8, v8, v192
	v_add_f32_e32 v9, v9, v193
	ds_read_b128 v[190:193], v250 offset:23552
	s_waitcnt lgkmcnt(7)
	v_add_f32_e32 v122, v122, v162
	v_add_f32_e32 v123, v123, v163
	v_add_f32_e32 v124, v124, v164
	v_add_f32_e32 v125, v125, v165
	ds_read_b128 v[162:165], v250 offset:24576
	s_waitcnt lgkmcnt(7)
	v_add_f32_e32 v126, v126, v166
	v_add_f32_e32 v127, v127, v167
	v_add_f32_e32 v128, v128, v168
	v_add_f32_e32 v129, v129, v169
	ds_read_b128 v[166:169], v250 offset:25600
	s_waitcnt lgkmcnt(7)
	v_add_f32_e32 v106, v106, v170
	v_add_f32_e32 v107, v107, v171
	v_add_f32_e32 v108, v108, v172
	v_add_f32_e32 v109, v109, v173
	ds_read_b128 v[170:173], v250 offset:26624
	s_waitcnt lgkmcnt(7)
	v_add_f32_e32 v110, v110, v174
	v_add_f32_e32 v111, v111, v175
	v_add_f32_e32 v112, v112, v176
	v_add_f32_e32 v113, v113, v177
	ds_read_b128 v[174:177], v250 offset:27648
	s_waitcnt lgkmcnt(7)
	v_add_f32_e32 v90, v90, v178
	v_add_f32_e32 v91, v91, v179
	v_add_f32_e32 v92, v92, v180
	v_add_f32_e32 v93, v93, v181
	ds_read_b128 v[178:181], v250 offset:28672
	s_waitcnt lgkmcnt(7)
	v_add_f32_e32 v94, v94, v182
	v_add_f32_e32 v95, v95, v183
	v_add_f32_e32 v96, v96, v184
	v_add_f32_e32 v97, v97, v185
	ds_read_b128 v[182:185], v250 offset:29696
	s_waitcnt lgkmcnt(7)
	v_add_f32_e32 v74, v74, v186
	v_add_f32_e32 v75, v75, v187
	v_add_f32_e32 v76, v76, v188
	v_add_f32_e32 v77, v77, v189
	ds_read_b128 v[186:189], v250 offset:30720
	s_waitcnt lgkmcnt(7)
	v_add_f32_e32 v78, v78, v190
	v_add_f32_e32 v79, v79, v191
	v_add_f32_e32 v80, v80, v192
	v_add_f32_e32 v81, v81, v193
	ds_read_b128 v[190:193], v250 offset:31744
	s_waitcnt lgkmcnt(7)
	v_add_f32_e32 v58, v58, v162
	v_add_f32_e32 v59, v59, v163
	v_add_f32_e32 v60, v60, v164
	v_add_f32_e32 v61, v61, v165
	s_waitcnt lgkmcnt(6)
	v_add_f32_e32 v62, v62, v166
	v_add_f32_e32 v63, v63, v167
	v_add_f32_e32 v64, v64, v168
	v_add_f32_e32 v65, v65, v169
	s_waitcnt lgkmcnt(5)
	v_add_f32_e32 v42, v42, v170
	v_add_f32_e32 v43, v43, v171
	v_add_f32_e32 v44, v44, v172
	v_add_f32_e32 v45, v45, v173
	s_waitcnt lgkmcnt(4)
	v_add_f32_e32 v46, v46, v174
	v_add_f32_e32 v47, v47, v175
	v_add_f32_e32 v48, v48, v176
	v_add_f32_e32 v49, v49, v177
	s_waitcnt lgkmcnt(3)
	v_add_f32_e32 v26, v26, v178
	v_add_f32_e32 v27, v27, v179
	v_add_f32_e32 v28, v28, v180
	v_add_f32_e32 v29, v29, v181
	s_waitcnt lgkmcnt(2)
	v_add_f32_e32 v30, v30, v182
	v_add_f32_e32 v31, v31, v183
	v_add_f32_e32 v32, v32, v184
	v_add_f32_e32 v33, v33, v185
	s_waitcnt lgkmcnt(1)
	v_add_f32_e32 v10, v10, v186
	v_add_f32_e32 v11, v11, v187
	v_add_f32_e32 v12, v12, v188
	v_add_f32_e32 v13, v13, v189
	s_waitcnt lgkmcnt(0)
	v_add_f32_e32 v14, v14, v190
	v_add_f32_e32 v15, v15, v191
	v_add_f32_e32 v16, v16, v192
	v_add_f32_e32 v17, v17, v193
	global_load_dwordx4 v[162:165], v252, s[52:53]
	global_load_dwordx4 v[166:169], v252, s[52:53] offset:64
	global_load_dwordx4 v[170:173], v252, s[52:53] offset:128
	global_load_dwordx4 v[174:177], v252, s[52:53] offset:192
	global_load_dwordx4 v[178:181], v252, s[52:53] offset:256
	global_load_dwordx4 v[182:185], v252, s[52:53] offset:320
	global_load_dwordx4 v[186:189], v252, s[52:53] offset:384
	global_load_dwordx4 v[190:193], v252, s[52:53] offset:448
	v_mul_f32_e32 v248, v114, v114
	v_fmac_f32_e32 v248, v115, v115
	v_fmac_f32_e32 v248, v116, v116
	v_fmac_f32_e32 v248, v117, v117
	v_fmac_f32_e32 v248, v118, v118
	v_fmac_f32_e32 v248, v119, v119
	v_fmac_f32_e32 v248, v120, v120
	v_fmac_f32_e32 v248, v121, v121
	v_fmac_f32_e32 v248, v98, v98
	v_fmac_f32_e32 v248, v99, v99
	v_fmac_f32_e32 v248, v100, v100
	v_fmac_f32_e32 v248, v101, v101
	v_fmac_f32_e32 v248, v102, v102
	v_fmac_f32_e32 v248, v103, v103
	v_fmac_f32_e32 v248, v104, v104
	v_fmac_f32_e32 v248, v105, v105
	v_fmac_f32_e32 v248, v82, v82
	v_fmac_f32_e32 v248, v83, v83
	v_fmac_f32_e32 v248, v84, v84
	v_fmac_f32_e32 v248, v85, v85
	v_fmac_f32_e32 v248, v86, v86
	v_fmac_f32_e32 v248, v87, v87
	v_fmac_f32_e32 v248, v88, v88
	v_fmac_f32_e32 v248, v89, v89
	v_fmac_f32_e32 v248, v66, v66
	v_fmac_f32_e32 v248, v67, v67
	v_fmac_f32_e32 v248, v68, v68
	v_fmac_f32_e32 v248, v69, v69
	v_fmac_f32_e32 v248, v70, v70
	v_fmac_f32_e32 v248, v71, v71
	v_fmac_f32_e32 v248, v72, v72
	v_fmac_f32_e32 v248, v73, v73
	v_fmac_f32_e32 v248, v50, v50
	v_fmac_f32_e32 v248, v51, v51
	v_fmac_f32_e32 v248, v52, v52
	v_fmac_f32_e32 v248, v53, v53
	v_fmac_f32_e32 v248, v54, v54
	v_fmac_f32_e32 v248, v55, v55
	v_fmac_f32_e32 v248, v56, v56
	v_fmac_f32_e32 v248, v57, v57
	v_fmac_f32_e32 v248, v34, v34
	v_fmac_f32_e32 v248, v35, v35
	v_fmac_f32_e32 v248, v36, v36
	v_fmac_f32_e32 v248, v37, v37
	v_fmac_f32_e32 v248, v38, v38
	v_fmac_f32_e32 v248, v39, v39
	v_fmac_f32_e32 v248, v40, v40
	v_fmac_f32_e32 v248, v41, v41
	v_fmac_f32_e32 v248, v18, v18
	v_fmac_f32_e32 v248, v19, v19
	v_fmac_f32_e32 v248, v20, v20
	v_fmac_f32_e32 v248, v21, v21
	v_fmac_f32_e32 v248, v22, v22
	v_fmac_f32_e32 v248, v23, v23
	v_fmac_f32_e32 v248, v24, v24
	v_fmac_f32_e32 v248, v25, v25
	v_fmac_f32_e32 v248, v2, v2
	v_fmac_f32_e32 v248, v3, v3
	v_fmac_f32_e32 v248, v4, v4
	v_fmac_f32_e32 v248, v5, v5
	v_fmac_f32_e32 v248, v6, v6
	v_fmac_f32_e32 v248, v7, v7
	v_fmac_f32_e32 v248, v8, v8
	v_fmac_f32_e32 v248, v9, v9
	v_mul_f32_e32 v249, v122, v122
	v_fmac_f32_e32 v249, v123, v123
	v_fmac_f32_e32 v249, v124, v124
	v_fmac_f32_e32 v249, v125, v125
	v_fmac_f32_e32 v249, v126, v126
	v_fmac_f32_e32 v249, v127, v127
	v_fmac_f32_e32 v249, v128, v128
	v_fmac_f32_e32 v249, v129, v129
	v_fmac_f32_e32 v249, v106, v106
	v_fmac_f32_e32 v249, v107, v107
	v_fmac_f32_e32 v249, v108, v108
	v_fmac_f32_e32 v249, v109, v109
	v_fmac_f32_e32 v249, v110, v110
	v_fmac_f32_e32 v249, v111, v111
	v_fmac_f32_e32 v249, v112, v112
	v_fmac_f32_e32 v249, v113, v113
	v_fmac_f32_e32 v249, v90, v90
	v_fmac_f32_e32 v249, v91, v91
	v_fmac_f32_e32 v249, v92, v92
	v_fmac_f32_e32 v249, v93, v93
	v_fmac_f32_e32 v249, v94, v94
	v_fmac_f32_e32 v249, v95, v95
	v_fmac_f32_e32 v249, v96, v96
	v_fmac_f32_e32 v249, v97, v97
	v_fmac_f32_e32 v249, v74, v74
	v_fmac_f32_e32 v249, v75, v75
	v_fmac_f32_e32 v249, v76, v76
	v_fmac_f32_e32 v249, v77, v77
	v_fmac_f32_e32 v249, v78, v78
	v_fmac_f32_e32 v249, v79, v79
	v_fmac_f32_e32 v249, v80, v80
	v_fmac_f32_e32 v249, v81, v81
	v_fmac_f32_e32 v249, v58, v58
	v_fmac_f32_e32 v249, v59, v59
	v_fmac_f32_e32 v249, v60, v60
	v_fmac_f32_e32 v249, v61, v61
	v_fmac_f32_e32 v249, v62, v62
	v_fmac_f32_e32 v249, v63, v63
	v_fmac_f32_e32 v249, v64, v64
	v_fmac_f32_e32 v249, v65, v65
	v_fmac_f32_e32 v249, v42, v42
	v_fmac_f32_e32 v249, v43, v43
	v_fmac_f32_e32 v249, v44, v44
	v_fmac_f32_e32 v249, v45, v45
	v_fmac_f32_e32 v249, v46, v46
	v_fmac_f32_e32 v249, v47, v47
	v_fmac_f32_e32 v249, v48, v48
	v_fmac_f32_e32 v249, v49, v49
	v_fmac_f32_e32 v249, v26, v26
	v_fmac_f32_e32 v249, v27, v27
	v_fmac_f32_e32 v249, v28, v28
	v_fmac_f32_e32 v249, v29, v29
	v_fmac_f32_e32 v249, v30, v30
	v_fmac_f32_e32 v249, v31, v31
	v_fmac_f32_e32 v249, v32, v32
	v_fmac_f32_e32 v249, v33, v33
	v_fmac_f32_e32 v249, v10, v10
	v_fmac_f32_e32 v249, v11, v11
	v_fmac_f32_e32 v249, v12, v12
	v_fmac_f32_e32 v249, v13, v13
	v_fmac_f32_e32 v249, v14, v14
	v_fmac_f32_e32 v249, v15, v15
	v_fmac_f32_e32 v249, v16, v16
	v_fmac_f32_e32 v249, v17, v17
	s_nop 1
	v_permlane16_swap_b32_e32 v248, v249
	v_add_f32_e32 v248, v248, v249
	v_mov_b32_e32 v249, v248
	s_nop 1
	v_permlane32_swap_b32_e32 v248, v249
	v_add_f32_e32 v248, v248, v249
	v_mov_b32_e32 v249, v248
	s_nop 1
	v_permlane16_swap_b32_e32 v248, v249
	s_nop 0
	v_fmamk_f32 v248, v248, 0x3b800000, v214
	v_fmamk_f32 v249, v249, 0x3b800000, v214
	v_rsq_f32_e32 v248, v248
	v_rsq_f32_e32 v249, v249
	v_and_b32_e32 v250, 15, v211
	v_lshrrev_b32_e32 v251, 4, v211
	v_mul_f32_e32 v248, 0x3f4ccccd, v248
	v_mul_f32_e32 v249, 0x3f4ccccd, v249
	v_xor_b32_e32 v251, v250, v251
	v_lshlrev_b32_e32 v251, 4, v251
	v_lshl_add_u32 v251, v250, 10, v251
	v_add_u32_e32 v251, s95, v251
	s_waitcnt vmcnt(8)
	v_mul_f32_e32 v50, v50, v248
	v_mul_f32_e32 v51, v51, v248
	v_mul_f32_e32 v52, v52, v248
	v_mul_f32_e32 v53, v53, v248
	v_mul_f32_e32 v50, v50, v194
	v_mul_f32_e32 v51, v51, v195
	v_mul_f32_e32 v52, v52, v196
	v_mul_f32_e32 v53, v53, v197
	v_xor_b32_e32 v253, 0x200, v251
	ds_write_b128 v253, v[50:53]
	v_mul_f32_e32 v58, v58, v249
	v_mul_f32_e32 v59, v59, v249
	v_mul_f32_e32 v60, v60, v249
	v_mul_f32_e32 v61, v61, v249
	v_mul_f32_e32 v58, v58, v194
	v_mul_f32_e32 v59, v59, v195
	v_mul_f32_e32 v60, v60, v196
	v_mul_f32_e32 v61, v61, v197
	v_xor_b32_e32 v253, 0x200, v251
	ds_write_b128 v253, v[58:61] offset:16384
	v_mul_f32_e32 v54, v54, v248
	v_mul_f32_e32 v55, v55, v248
	v_mul_f32_e32 v56, v56, v248
	v_mul_f32_e32 v57, v57, v248
	v_mul_f32_e32 v54, v54, v198
	v_mul_f32_e32 v55, v55, v199
	v_mul_f32_e32 v56, v56, v200
	v_mul_f32_e32 v57, v57, v201
	v_xor_b32_e32 v253, 0x240, v251
	ds_write_b128 v253, v[54:57]
	v_mul_f32_e32 v62, v62, v249
	v_mul_f32_e32 v63, v63, v249
	v_mul_f32_e32 v64, v64, v249
	v_mul_f32_e32 v65, v65, v249
	v_mul_f32_e32 v62, v62, v198
	v_mul_f32_e32 v63, v63, v199
	v_mul_f32_e32 v64, v64, v200
	v_mul_f32_e32 v65, v65, v201
	v_xor_b32_e32 v253, 0x240, v251
	ds_write_b128 v253, v[62:65] offset:16384
	v_mul_f32_e32 v34, v34, v248
	v_mul_f32_e32 v35, v35, v248
	v_mul_f32_e32 v36, v36, v248
	v_mul_f32_e32 v37, v37, v248
	v_mul_f32_e32 v34, v34, v202
	v_mul_f32_e32 v35, v35, v203
	v_mul_f32_e32 v36, v36, v204
	v_mul_f32_e32 v37, v37, v205
	v_xor_b32_e32 v253, 0x280, v251
	ds_write_b128 v253, v[34:37]
	v_mul_f32_e32 v42, v42, v249
	v_mul_f32_e32 v43, v43, v249
	v_mul_f32_e32 v44, v44, v249
	v_mul_f32_e32 v45, v45, v249
	v_mul_f32_e32 v42, v42, v202
	v_mul_f32_e32 v43, v43, v203
	v_mul_f32_e32 v44, v44, v204
	v_mul_f32_e32 v45, v45, v205
	v_xor_b32_e32 v253, 0x280, v251
	ds_write_b128 v253, v[42:45] offset:16384
	v_mul_f32_e32 v38, v38, v248
	v_mul_f32_e32 v39, v39, v248
	v_mul_f32_e32 v40, v40, v248
	v_mul_f32_e32 v41, v41, v248
	v_mul_f32_e32 v38, v38, v206
	v_mul_f32_e32 v39, v39, v207
	v_mul_f32_e32 v40, v40, v208
	v_mul_f32_e32 v41, v41, v209
	v_xor_b32_e32 v253, 0x2c0, v251
	ds_write_b128 v253, v[38:41]
	v_mul_f32_e32 v46, v46, v249
	v_mul_f32_e32 v47, v47, v249
	v_mul_f32_e32 v48, v48, v249
	v_mul_f32_e32 v49, v49, v249
	v_mul_f32_e32 v46, v46, v206
	v_mul_f32_e32 v47, v47, v207
	v_mul_f32_e32 v48, v48, v208
	v_mul_f32_e32 v49, v49, v209
	v_xor_b32_e32 v253, 0x2c0, v251
	ds_write_b128 v253, v[46:49] offset:16384
	v_mul_f32_e32 v18, v18, v248
	v_mul_f32_e32 v19, v19, v248
	v_mul_f32_e32 v20, v20, v248
	v_mul_f32_e32 v21, v21, v248
	v_mul_f32_e32 v18, v18, v232
	v_mul_f32_e32 v19, v19, v233
	v_mul_f32_e32 v20, v20, v234
	v_mul_f32_e32 v21, v21, v235
	v_xor_b32_e32 v253, 0x300, v251
	ds_write_b128 v253, v[18:21]
	v_mul_f32_e32 v26, v26, v249
	v_mul_f32_e32 v27, v27, v249
	v_mul_f32_e32 v28, v28, v249
	v_mul_f32_e32 v29, v29, v249
	v_mul_f32_e32 v26, v26, v232
	v_mul_f32_e32 v27, v27, v233
	v_mul_f32_e32 v28, v28, v234
	v_mul_f32_e32 v29, v29, v235
	v_xor_b32_e32 v253, 0x300, v251
	ds_write_b128 v253, v[26:29] offset:16384
	v_mul_f32_e32 v22, v22, v248
	v_mul_f32_e32 v23, v23, v248
	v_mul_f32_e32 v24, v24, v248
	v_mul_f32_e32 v25, v25, v248
	v_mul_f32_e32 v22, v22, v236
	v_mul_f32_e32 v23, v23, v237
	v_mul_f32_e32 v24, v24, v238
	v_mul_f32_e32 v25, v25, v239
	v_xor_b32_e32 v253, 0x340, v251
	ds_write_b128 v253, v[22:25]
	v_mul_f32_e32 v30, v30, v249
	v_mul_f32_e32 v31, v31, v249
	v_mul_f32_e32 v32, v32, v249
	v_mul_f32_e32 v33, v33, v249
	v_mul_f32_e32 v30, v30, v236
	v_mul_f32_e32 v31, v31, v237
	v_mul_f32_e32 v32, v32, v238
	v_mul_f32_e32 v33, v33, v239
	v_xor_b32_e32 v253, 0x340, v251
	ds_write_b128 v253, v[30:33] offset:16384
	v_mul_f32_e32 v2, v2, v248
	v_mul_f32_e32 v3, v3, v248
	v_mul_f32_e32 v4, v4, v248
	v_mul_f32_e32 v5, v5, v248
	v_mul_f32_e32 v2, v2, v240
	v_mul_f32_e32 v3, v3, v241
	v_mul_f32_e32 v4, v4, v242
	v_mul_f32_e32 v5, v5, v243
	v_xor_b32_e32 v253, 0x380, v251
	ds_write_b128 v253, v[2:5]
	v_mul_f32_e32 v10, v10, v249
	v_mul_f32_e32 v11, v11, v249
	v_mul_f32_e32 v12, v12, v249
	v_mul_f32_e32 v13, v13, v249
	v_mul_f32_e32 v10, v10, v240
	v_mul_f32_e32 v11, v11, v241
	v_mul_f32_e32 v12, v12, v242
	v_mul_f32_e32 v13, v13, v243
	v_xor_b32_e32 v253, 0x380, v251
	ds_write_b128 v253, v[10:13] offset:16384
	v_mul_f32_e32 v6, v6, v248
	v_mul_f32_e32 v7, v7, v248
	v_mul_f32_e32 v8, v8, v248
	v_mul_f32_e32 v9, v9, v248
	v_mul_f32_e32 v6, v6, v244
	v_mul_f32_e32 v7, v7, v245
	v_mul_f32_e32 v8, v8, v246
	v_mul_f32_e32 v9, v9, v247
	v_xor_b32_e32 v253, 0x3c0, v251
	ds_write_b128 v253, v[6:9]
	v_mul_f32_e32 v14, v14, v249
	v_mul_f32_e32 v15, v15, v249
	v_mul_f32_e32 v16, v16, v249
	v_mul_f32_e32 v17, v17, v249
	v_mul_f32_e32 v14, v14, v244
	v_mul_f32_e32 v15, v15, v245
	v_mul_f32_e32 v16, v16, v246
	v_mul_f32_e32 v17, v17, v247
	v_xor_b32_e32 v253, 0x3c0, v251
	ds_write_b128 v253, v[14:17] offset:16384
	s_waitcnt vmcnt(0)
	v_mul_f32_e32 v114, v114, v248
	v_mul_f32_e32 v115, v115, v248
	v_mul_f32_e32 v116, v116, v248
	v_mul_f32_e32 v117, v117, v248
	v_mul_f32_e32 v114, v114, v162
	v_mul_f32_e32 v115, v115, v163
	v_mul_f32_e32 v116, v116, v164
	v_mul_f32_e32 v117, v117, v165
	ds_write_b128 v251, v[114:117]
	v_mul_f32_e32 v122, v122, v249
	v_mul_f32_e32 v123, v123, v249
	v_mul_f32_e32 v124, v124, v249
	v_mul_f32_e32 v125, v125, v249
	v_mul_f32_e32 v122, v122, v162
	v_mul_f32_e32 v123, v123, v163
	v_mul_f32_e32 v124, v124, v164
	v_mul_f32_e32 v125, v125, v165
	ds_write_b128 v251, v[122:125] offset:16384
	v_mul_f32_e32 v118, v118, v248
	v_mul_f32_e32 v119, v119, v248
	v_mul_f32_e32 v120, v120, v248
	v_mul_f32_e32 v121, v121, v248
	v_mul_f32_e32 v118, v118, v166
	v_mul_f32_e32 v119, v119, v167
	v_mul_f32_e32 v120, v120, v168
	v_mul_f32_e32 v121, v121, v169
	v_xor_b32_e32 v253, 64, v251
	ds_write_b128 v253, v[118:121]
	v_mul_f32_e32 v126, v126, v249
	v_mul_f32_e32 v127, v127, v249
	v_mul_f32_e32 v128, v128, v249
	v_mul_f32_e32 v129, v129, v249
	v_mul_f32_e32 v126, v126, v166
	v_mul_f32_e32 v127, v127, v167
	v_mul_f32_e32 v128, v128, v168
	v_mul_f32_e32 v129, v129, v169
	v_xor_b32_e32 v253, 64, v251
	ds_write_b128 v253, v[126:129] offset:16384
	v_mul_f32_e32 v98, v98, v248
	v_mul_f32_e32 v99, v99, v248
	v_mul_f32_e32 v100, v100, v248
	v_mul_f32_e32 v101, v101, v248
	v_mul_f32_e32 v98, v98, v170
	v_mul_f32_e32 v99, v99, v171
	v_mul_f32_e32 v100, v100, v172
	v_mul_f32_e32 v101, v101, v173
	v_xor_b32_e32 v253, 0x80, v251
	ds_write_b128 v253, v[98:101]
	v_mul_f32_e32 v106, v106, v249
	v_mul_f32_e32 v107, v107, v249
	v_mul_f32_e32 v108, v108, v249
	v_mul_f32_e32 v109, v109, v249
	v_mul_f32_e32 v106, v106, v170
	v_mul_f32_e32 v107, v107, v171
	v_mul_f32_e32 v108, v108, v172
	v_mul_f32_e32 v109, v109, v173
	v_xor_b32_e32 v253, 0x80, v251
	ds_write_b128 v253, v[106:109] offset:16384
	v_mul_f32_e32 v102, v102, v248
	v_mul_f32_e32 v103, v103, v248
	v_mul_f32_e32 v104, v104, v248
	v_mul_f32_e32 v105, v105, v248
	v_mul_f32_e32 v102, v102, v174
	v_mul_f32_e32 v103, v103, v175
	v_mul_f32_e32 v104, v104, v176
	v_mul_f32_e32 v105, v105, v177
	v_xor_b32_e32 v253, 0xc0, v251
	ds_write_b128 v253, v[102:105]
	v_mul_f32_e32 v110, v110, v249
	v_mul_f32_e32 v111, v111, v249
	v_mul_f32_e32 v112, v112, v249
	v_mul_f32_e32 v113, v113, v249
	v_mul_f32_e32 v110, v110, v174
	v_mul_f32_e32 v111, v111, v175
	v_mul_f32_e32 v112, v112, v176
	v_mul_f32_e32 v113, v113, v177
	v_xor_b32_e32 v253, 0xc0, v251
	ds_write_b128 v253, v[110:113] offset:16384
	v_mul_f32_e32 v82, v82, v248
	v_mul_f32_e32 v83, v83, v248
	v_mul_f32_e32 v84, v84, v248
	v_mul_f32_e32 v85, v85, v248
	v_mul_f32_e32 v82, v82, v178
	v_mul_f32_e32 v83, v83, v179
	v_mul_f32_e32 v84, v84, v180
	v_mul_f32_e32 v85, v85, v181
	v_xor_b32_e32 v253, 0x100, v251
	ds_write_b128 v253, v[82:85]
	v_mul_f32_e32 v90, v90, v249
	v_mul_f32_e32 v91, v91, v249
	v_mul_f32_e32 v92, v92, v249
	v_mul_f32_e32 v93, v93, v249
	v_mul_f32_e32 v90, v90, v178
	v_mul_f32_e32 v91, v91, v179
	v_mul_f32_e32 v92, v92, v180
	v_mul_f32_e32 v93, v93, v181
	v_xor_b32_e32 v253, 0x100, v251
	ds_write_b128 v253, v[90:93] offset:16384
	v_mul_f32_e32 v86, v86, v248
	v_mul_f32_e32 v87, v87, v248
	v_mul_f32_e32 v88, v88, v248
	v_mul_f32_e32 v89, v89, v248
	v_mul_f32_e32 v86, v86, v182
	v_mul_f32_e32 v87, v87, v183
	v_mul_f32_e32 v88, v88, v184
	v_mul_f32_e32 v89, v89, v185
	v_xor_b32_e32 v253, 0x140, v251
	ds_write_b128 v253, v[86:89]
	v_mul_f32_e32 v94, v94, v249
	v_mul_f32_e32 v95, v95, v249
	v_mul_f32_e32 v96, v96, v249
	v_mul_f32_e32 v97, v97, v249
	v_mul_f32_e32 v94, v94, v182
	v_mul_f32_e32 v95, v95, v183
	v_mul_f32_e32 v96, v96, v184
	v_mul_f32_e32 v97, v97, v185
	v_xor_b32_e32 v253, 0x140, v251
	ds_write_b128 v253, v[94:97] offset:16384
	v_mul_f32_e32 v66, v66, v248
	v_mul_f32_e32 v67, v67, v248
	v_mul_f32_e32 v68, v68, v248
	v_mul_f32_e32 v69, v69, v248
	v_mul_f32_e32 v66, v66, v186
	v_mul_f32_e32 v67, v67, v187
	v_mul_f32_e32 v68, v68, v188
	v_mul_f32_e32 v69, v69, v189
	v_xor_b32_e32 v253, 0x180, v251
	ds_write_b128 v253, v[66:69]
	v_mul_f32_e32 v74, v74, v249
	v_mul_f32_e32 v75, v75, v249
	v_mul_f32_e32 v76, v76, v249
	v_mul_f32_e32 v77, v77, v249
	v_mul_f32_e32 v74, v74, v186
	v_mul_f32_e32 v75, v75, v187
	v_mul_f32_e32 v76, v76, v188
	v_mul_f32_e32 v77, v77, v189
	v_xor_b32_e32 v253, 0x180, v251
	ds_write_b128 v253, v[74:77] offset:16384
	v_mul_f32_e32 v70, v70, v248
	v_mul_f32_e32 v71, v71, v248
	v_mul_f32_e32 v72, v72, v248
	v_mul_f32_e32 v73, v73, v248
	v_mul_f32_e32 v70, v70, v190
	v_mul_f32_e32 v71, v71, v191
	v_mul_f32_e32 v72, v72, v192
	v_mul_f32_e32 v73, v73, v193
	v_xor_b32_e32 v253, 0x1c0, v251
	ds_write_b128 v253, v[70:73]
	v_mul_f32_e32 v78, v78, v249
	v_mul_f32_e32 v79, v79, v249
	v_mul_f32_e32 v80, v80, v249
	v_mul_f32_e32 v81, v81, v249
	v_mul_f32_e32 v78, v78, v190
	v_mul_f32_e32 v79, v79, v191
	v_mul_f32_e32 v80, v80, v192
	v_mul_f32_e32 v81, v81, v193
	v_xor_b32_e32 v253, 0x1c0, v251
	ds_write_b128 v253, v[78:81] offset:16384
	s_waitcnt lgkmcnt(0)
.Lat_ep_fin:
	s_waitcnt vmcnt(0)
	v_mov_b32_e32 v30, v130
	v_mov_b32_e32 v31, v131
	v_mov_b32_e32 v32, v132
	v_mov_b32_e32 v33, v133
	v_mov_b32_e32 v26, v134
	v_mov_b32_e32 v27, v135
	v_mov_b32_e32 v28, v136
	v_mov_b32_e32 v29, v137
	v_mov_b32_e32 v22, v138
	v_mov_b32_e32 v23, v139
	v_mov_b32_e32 v24, v140
	v_mov_b32_e32 v25, v141
	v_mov_b32_e32 v18, v142
	v_mov_b32_e32 v19, v143
	v_mov_b32_e32 v20, v144
	v_mov_b32_e32 v21, v145
	v_mov_b32_e32 v14, v146
	v_mov_b32_e32 v15, v147
	v_mov_b32_e32 v16, v148
	v_mov_b32_e32 v17, v149
	v_mov_b32_e32 v10, v150
	v_mov_b32_e32 v11, v151
	v_mov_b32_e32 v12, v152
	v_mov_b32_e32 v13, v153
	v_mov_b32_e32 v6, v154
	v_mov_b32_e32 v7, v155
	v_mov_b32_e32 v8, v156
	v_mov_b32_e32 v9, v157
	v_mov_b32_e32 v2, v158
	v_mov_b32_e32 v3, v159
	v_mov_b32_e32 v4, v160
	v_mov_b32_e32 v5, v161
	v_readlane_b32 s6, v254, 27
	s_nop 1
	v_add_u32_e32 v164, s6, v218
	v_add_u32_e32 v35, s3, v164
	v_lshlrev_b32_e32 v34, 13, v35
	v_lshrrev_b32_e32 v35, 19, v35
	s_branch .LBB0_256
.Lat_inactive:
	s_add_i32 m0, s71, 0x0
	s_nop 0
	global_load_lds_dwordx4 v231, s[50:51]
	s_add_i32 m0, s71, 0x400
	s_nop 0
	global_load_lds_dwordx4 v229, s[50:51]
	s_add_i32 m0, s71, 0x800
	s_nop 0
	global_load_lds_dwordx4 v227, s[50:51]
	s_add_i32 m0, s71, 0xc00
	s_nop 0
	global_load_lds_dwordx4 v225, s[50:51]
	s_add_i32 m0, s71, 0x1000
	s_nop 0
	global_load_lds_dwordx4 v230, s[50:51]
	s_add_i32 m0, s71, 0x1400
	s_nop 0
	global_load_lds_dwordx4 v228, s[50:51]
	s_add_i32 m0, s71, 0x1800
	s_nop 0
	global_load_lds_dwordx4 v226, s[50:51]
	s_add_i32 m0, s71, 0x1c00
	s_nop 0
	global_load_lds_dwordx4 v224, s[50:51]
	s_branch .Lat_next
.LBB0_359:
	v_readlane_b32 s90, v254, 11
	v_readlane_b32 s94, v254, 22
	v_readlane_b32 s87, v254, 18
	v_readlane_b32 s88, v254, 14
	v_readlane_b32 s91, v254, 12
	v_readlane_b32 s89, v254, 17
	v_readlane_b32 s95, v254, 23
